# own: gate loads issued at item start instead of epilogue
# baseline (speedup 1.0000x reference)
.LBB0_277:
	s_ashr_i32 s0, s23, 7
	s_ashr_i32 s1, s0, 31
	s_lshl_b64 s[0:1], s[0:1], 22
	s_waitcnt vmcnt(0)
	v_lshlrev_b32_e32 v20, 10, v140
	v_mov_b32_e32 v21, v121
	v_lshl_add_u64 v[20:21], s[0:1], 0, v[20:21]
	v_lshlrev_b64 v[20:21], 1, v[20:21]
	s_lshl_b32 s0, s14, 7
	v_lshl_add_u64 v[22:23], s[70:71], 0, v[20:21]
	s_and_b32 s12, s0, 0x380
	v_lshl_add_u64 v[22:23], v[22:23], 0, s[12:13]
	v_mov_b32_e32 v75, v121
	v_lshl_add_u64 v[140:141], v[22:23], 0, v[74:75]
	v_max_f32_e32 v22, v132, v132
	v_max_f32_e32 v23, v71, v71
	v_max_f32_e32 v30, v23, v22
	v_sub_f32_e32 v22, v71, v30
	v_sub_f32_e32 v23, v132, v30
	v_exp_f32_e32 v22, v22
	v_exp_f32_e32 v23, v23
	v_max_f32_e32 v24, v148, v148
	v_max_f32_e32 v24, v30, v24
	v_mov_b32_e32 v132, v114
	v_sub_f32_e32 v30, v30, v24
	v_exp_f32_e32 v139, v30
	v_pk_mul_f32 v[30:31], v[132:133], v[22:23]
	v_sub_f32_e32 v65, v148, v24
	v_pk_fma_f32 v[132:133], v[132:133], v[22:23], v[30:31] op_sel_hi:[1,1,0]
	v_lshlrev_b32_e32 v26, 16, v142
	v_exp_f32_e32 v132, v65
	v_and_b32_e32 v27, 0xffff0000, v142
	v_lshlrev_b32_e32 v28, 16, v143
	v_and_b32_e32 v29, 0xffff0000, v143
	v_max_f32_e32 v25, v152, v152
	v_pk_mul_f32 v[32:33], v[30:31], v[26:27] op_sel:[1,0]
	v_max_f32_e32 v25, v24, v25
	v_mov_b32_e32 v26, v139
	v_pk_mul_f32 v[148:149], v[30:31], v[28:29] op_sel:[1,0]
	v_pk_fma_f32 v[32:33], v[44:45], v[22:23], v[32:33] op_sel_hi:[1,0,1]
	v_sub_f32_e32 v24, v24, v25
	v_pk_fma_f32 v[44:45], v[46:47], v[22:23], v[148:149] op_sel_hi:[1,0,1]
	v_pk_mul_f32 v[46:47], v[26:27], v[32:33] op_sel_hi:[0,1]
	v_pk_mul_f32 v[32:33], v[138:139], v[132:133]
	v_sub_f32_e32 v67, v152, v25
	v_exp_f32_e32 v137, v24
	v_pk_fma_f32 v[132:133], v[138:139], v[132:133], v[32:33] op_sel_hi:[1,1,0]
	v_lshlrev_b32_e32 v34, 16, v150
	v_exp_f32_e32 v132, v67
	v_and_b32_e32 v35, 0xffff0000, v150
	v_mov_b32_e32 v28, v137
	v_pk_fma_f32 v[34:35], v[32:33], v[34:35], v[46:47] op_sel_hi:[0,1,1]
	v_pk_mul_f32 v[138:139], v[28:29], v[34:35] op_sel_hi:[0,1]
	v_pk_mul_f32 v[34:35], v[136:137], v[132:133]
	v_lshlrev_b32_e32 v142, 16, v151
	v_and_b32_e32 v143, 0xffff0000, v151
	v_pk_mul_f32 v[44:45], v[26:27], v[44:45] op_sel_hi:[0,1]
	v_add_f32_e32 v23, v34, v35
	v_pk_fma_f32 v[46:47], v[32:33], v[142:143], v[44:45] op_sel_hi:[0,1,1]
	v_rcp_f32_e32 v44, v23
	v_lshlrev_b32_e32 v150, 16, v154
	v_and_b32_e32 v151, 0xffff0000, v154
	v_lshlrev_b32_e32 v154, 16, v155
	v_and_b32_e32 v155, 0xffff0000, v155
	v_pk_mul_f32 v[46:47], v[28:29], v[46:47] op_sel_hi:[0,1]
	v_pk_fma_f32 v[132:133], v[34:35], v[150:151], v[138:139] op_sel_hi:[0,1,1]
	v_pk_fma_f32 v[46:47], v[34:35], v[154:155], v[46:47] op_sel_hi:[0,1,1]
	v_pk_mul_f32 v[132:133], v[44:45], v[132:133] op_sel_hi:[0,1]
	v_pk_mul_f32 v[46:47], v[44:45], v[46:47] op_sel_hi:[0,1]
	v_readlane_b32 s16, v254, 2
	v_readlane_b32 s17, v254, 3
	s_add_i32 s23, s23, s3
	s_cmpk_lt_i32 s23, 0x800
	v_lshl_add_u64 v[24:25], s[16:17], 0, v[20:21]
	v_lshl_add_u64 v[24:25], v[24:25], 0, s[12:13]
	v_lshl_add_u64 v[24:25], v[24:25], 0, v[74:75]
	v_or_b32_e32 v20, 0x8000, v20
	v_readlane_b32 s18, v254, 4
	v_readlane_b32 s19, v254, 5
	v_mov_b32_e32 v156, v234
	v_mov_b32_e32 v157, v235
	v_lshlrev_b32_e32 v136, 16, v156
	v_and_b32_e32 v137, 0xffff0000, v156
	v_lshlrev_b32_e32 v138, 16, v157
	v_and_b32_e32 v139, 0xffff0000, v157
	v_mul_f32_e32 v23, 0xbfb8aa3b, v136
	v_mul_f32_e32 v27, 0xbfb8aa3b, v137
	v_mul_f32_e32 v29, 0xbfb8aa3b, v138
	v_mul_f32_e32 v45, 0xbfb8aa3b, v139
	v_exp_f32_e32 v23, v23
	v_exp_f32_e32 v27, v27
	v_exp_f32_e32 v29, v29
	v_exp_f32_e32 v45, v45
	v_add_f32_e32 v23, 1.0, v23
	v_add_f32_e32 v27, 1.0, v27
	v_add_f32_e32 v29, 1.0, v29
	v_add_f32_e32 v45, 1.0, v45
	v_rcp_f32_e32 v142, v23
	v_rcp_f32_e32 v143, v27
	v_rcp_f32_e32 v148, v29
	v_rcp_f32_e32 v149, v45
	v_pk_mul_f32 v[132:133], v[132:133], v[136:137]
	v_pk_mul_f32 v[46:47], v[46:47], v[138:139]
	v_pk_mul_f32 v[132:133], v[132:133], v[142:143]
	v_pk_mul_f32 v[46:47], v[46:47], v[148:149]
	v_cvt_pk_bf16_f32 v132, v132, v133
	v_cvt_pk_bf16_f32 v133, v46, v47
	global_store_dwordx2 v[24:25], v[132:133], off offset:1024
	v_lshlrev_b32_e32 v132, 16, v128
	v_and_b32_e32 v133, 0xffff0000, v128
	v_lshlrev_b32_e32 v128, 16, v129
	v_and_b32_e32 v129, 0xffff0000, v129
	v_pk_mul_f32 v[132:133], v[30:31], v[132:133] op_sel:[1,0]
	v_pk_mul_f32 v[128:129], v[30:31], v[128:129] op_sel:[1,0]
	v_pk_fma_f32 v[40:41], v[40:41], v[22:23], v[132:133] op_sel_hi:[1,0,1]
	v_pk_fma_f32 v[42:43], v[42:43], v[22:23], v[128:129] op_sel_hi:[1,0,1]
	v_lshlrev_b32_e32 v136, 16, v130
	v_and_b32_e32 v137, 0xffff0000, v130
	v_lshlrev_b32_e32 v130, 16, v131
	v_and_b32_e32 v131, 0xffff0000, v131
	v_pk_mul_f32 v[40:41], v[26:27], v[40:41] op_sel_hi:[0,1]
	v_pk_mul_f32 v[42:43], v[26:27], v[42:43] op_sel_hi:[0,1]
	v_pk_fma_f32 v[40:41], v[32:33], v[136:137], v[40:41] op_sel_hi:[0,1,1]
	v_pk_fma_f32 v[42:43], v[32:33], v[130:131], v[42:43] op_sel_hi:[0,1,1]
	v_lshlrev_b32_e32 v138, 16, v134
	v_and_b32_e32 v139, 0xffff0000, v134
	v_lshlrev_b32_e32 v134, 16, v135
	v_and_b32_e32 v135, 0xffff0000, v135
	v_pk_mul_f32 v[40:41], v[28:29], v[40:41] op_sel_hi:[0,1]
	v_pk_mul_f32 v[42:43], v[28:29], v[42:43] op_sel_hi:[0,1]
	v_pk_fma_f32 v[40:41], v[34:35], v[138:139], v[40:41] op_sel_hi:[0,1,1]
	v_pk_fma_f32 v[42:43], v[34:35], v[134:135], v[42:43] op_sel_hi:[0,1,1]
	v_pk_mul_f32 v[40:41], v[44:45], v[40:41] op_sel_hi:[0,1]
	v_pk_mul_f32 v[42:43], v[44:45], v[42:43] op_sel_hi:[0,1]
	v_mov_b32_e32 v46, v236
	v_mov_b32_e32 v47, v237
	v_lshlrev_b32_e32 v128, 16, v46
	v_and_b32_e32 v129, 0xffff0000, v46
	v_lshlrev_b32_e32 v46, 16, v47
	v_and_b32_e32 v47, 0xffff0000, v47
	v_mul_f32_e32 v23, 0xbfb8aa3b, v128
	v_mul_f32_e32 v27, 0xbfb8aa3b, v129
	v_mul_f32_e32 v29, 0xbfb8aa3b, v46
	v_mul_f32_e32 v45, 0xbfb8aa3b, v47
	v_exp_f32_e32 v23, v23
	v_exp_f32_e32 v27, v27
	v_exp_f32_e32 v29, v29
	v_exp_f32_e32 v45, v45
	v_add_f32_e32 v23, 1.0, v23
	v_add_f32_e32 v27, 1.0, v27
	v_add_f32_e32 v29, 1.0, v29
	v_add_f32_e32 v45, 1.0, v45
	v_rcp_f32_e32 v130, v23
	v_rcp_f32_e32 v131, v27
	v_rcp_f32_e32 v132, v29
	v_rcp_f32_e32 v133, v45
	v_pk_mul_f32 v[40:41], v[40:41], v[128:129]
	v_pk_mul_f32 v[42:43], v[42:43], v[46:47]
	v_pk_mul_f32 v[40:41], v[40:41], v[130:131]
	v_pk_mul_f32 v[42:43], v[42:43], v[132:133]
	v_cvt_pk_bf16_f32 v40, v40, v41
	v_cvt_pk_bf16_f32 v41, v42, v43
	global_store_dwordx2 v[24:25], v[40:41], off offset:1056
	v_lshlrev_b32_e32 v42, 16, v118
	v_and_b32_e32 v43, 0xffff0000, v118
	v_lshlrev_b32_e32 v46, 16, v119
	v_and_b32_e32 v47, 0xffff0000, v119
	v_pk_mul_f32 v[42:43], v[30:31], v[42:43] op_sel:[1,0]
	v_pk_mul_f32 v[46:47], v[30:31], v[46:47] op_sel:[1,0]
	v_pk_fma_f32 v[36:37], v[36:37], v[22:23], v[42:43] op_sel_hi:[1,0,1]
	v_pk_fma_f32 v[38:39], v[38:39], v[22:23], v[46:47] op_sel_hi:[1,0,1]
	v_lshlrev_b32_e32 v118, 16, v124
	v_and_b32_e32 v119, 0xffff0000, v124
	v_lshlrev_b32_e32 v124, 16, v125
	v_and_b32_e32 v125, 0xffff0000, v125
	v_pk_mul_f32 v[36:37], v[26:27], v[36:37] op_sel_hi:[0,1]
	v_pk_mul_f32 v[38:39], v[26:27], v[38:39] op_sel_hi:[0,1]
	v_pk_fma_f32 v[36:37], v[32:33], v[118:119], v[36:37] op_sel_hi:[0,1,1]
	v_pk_fma_f32 v[38:39], v[32:33], v[124:125], v[38:39] op_sel_hi:[0,1,1]
	v_lshlrev_b32_e32 v128, 16, v126
	v_and_b32_e32 v129, 0xffff0000, v126
	v_lshlrev_b32_e32 v126, 16, v127
	v_and_b32_e32 v127, 0xffff0000, v127
	v_pk_mul_f32 v[36:37], v[28:29], v[36:37] op_sel_hi:[0,1]
	v_pk_mul_f32 v[38:39], v[28:29], v[38:39] op_sel_hi:[0,1]
	v_pk_fma_f32 v[36:37], v[34:35], v[128:129], v[36:37] op_sel_hi:[0,1,1]
	v_pk_fma_f32 v[38:39], v[34:35], v[126:127], v[38:39] op_sel_hi:[0,1,1]
	v_pk_mul_f32 v[36:37], v[44:45], v[36:37] op_sel_hi:[0,1]
	v_pk_mul_f32 v[38:39], v[44:45], v[38:39] op_sel_hi:[0,1]
	v_mov_b32_e32 v40, v238
	v_mov_b32_e32 v41, v239
	v_lshlrev_b32_e32 v42, 16, v40
	v_and_b32_e32 v43, 0xffff0000, v40
	v_lshlrev_b32_e32 v40, 16, v41
	v_and_b32_e32 v41, 0xffff0000, v41
	v_mul_f32_e32 v23, 0xbfb8aa3b, v42
	v_mul_f32_e32 v27, 0xbfb8aa3b, v43
	v_mul_f32_e32 v29, 0xbfb8aa3b, v40
	v_mul_f32_e32 v45, 0xbfb8aa3b, v41
	v_exp_f32_e32 v23, v23
	v_exp_f32_e32 v27, v27
	v_exp_f32_e32 v29, v29
	v_exp_f32_e32 v45, v45
	v_add_f32_e32 v23, 1.0, v23
	v_add_f32_e32 v27, 1.0, v27
	v_add_f32_e32 v29, 1.0, v29
	v_add_f32_e32 v45, 1.0, v45
	v_rcp_f32_e32 v46, v23
	v_rcp_f32_e32 v47, v27
	v_rcp_f32_e32 v118, v29
	v_rcp_f32_e32 v119, v45
	v_pk_mul_f32 v[36:37], v[36:37], v[42:43]
	v_pk_mul_f32 v[38:39], v[38:39], v[40:41]
	v_pk_mul_f32 v[36:37], v[36:37], v[46:47]
	v_pk_mul_f32 v[38:39], v[38:39], v[118:119]
	v_cvt_pk_bf16_f32 v36, v36, v37
	v_cvt_pk_bf16_f32 v37, v38, v39
	global_store_dwordx2 v[24:25], v[36:37], off offset:1088
	v_lshlrev_b32_e32 v38, 16, v112
	v_and_b32_e32 v39, 0xffff0000, v112
	v_lshlrev_b32_e32 v40, 16, v113
	v_and_b32_e32 v41, 0xffff0000, v113
	v_pk_mul_f32 v[38:39], v[30:31], v[38:39] op_sel:[1,0]
	v_pk_mul_f32 v[40:41], v[30:31], v[40:41] op_sel:[1,0]
	v_pk_fma_f32 v[16:17], v[16:17], v[22:23], v[38:39] op_sel_hi:[1,0,1]
	v_pk_fma_f32 v[18:19], v[18:19], v[22:23], v[40:41] op_sel_hi:[1,0,1]
	v_lshlrev_b32_e32 v42, 16, v110
	v_and_b32_e32 v43, 0xffff0000, v110
	v_lshlrev_b32_e32 v46, 16, v111
	v_and_b32_e32 v47, 0xffff0000, v111
	v_pk_mul_f32 v[16:17], v[26:27], v[16:17] op_sel_hi:[0,1]
	v_pk_mul_f32 v[18:19], v[26:27], v[18:19] op_sel_hi:[0,1]
	v_pk_fma_f32 v[16:17], v[32:33], v[42:43], v[16:17] op_sel_hi:[0,1,1]
	v_pk_fma_f32 v[18:19], v[32:33], v[46:47], v[18:19] op_sel_hi:[0,1,1]
	v_pk_mul_f32 v[16:17], v[28:29], v[16:17] op_sel_hi:[0,1]
	v_pk_mul_f32 v[18:19], v[28:29], v[18:19] op_sel_hi:[0,1]
	v_lshlrev_b32_e32 v110, 16, v116
	v_and_b32_e32 v111, 0xffff0000, v116
	v_lshlrev_b32_e32 v112, 16, v117
	v_and_b32_e32 v113, 0xffff0000, v117
	v_pk_fma_f32 v[16:17], v[34:35], v[110:111], v[16:17] op_sel_hi:[0,1,1]
	v_pk_fma_f32 v[18:19], v[34:35], v[112:113], v[18:19] op_sel_hi:[0,1,1]
	v_pk_mul_f32 v[16:17], v[44:45], v[16:17] op_sel_hi:[0,1]
	v_pk_mul_f32 v[18:19], v[44:45], v[18:19] op_sel_hi:[0,1]
	v_lshl_add_u64 v[116:117], s[70:71], 0, v[20:21]
	v_lshl_add_u64 v[116:117], v[116:117], 0, s[12:13]
	v_lshl_add_u64 v[30:31], v[116:117], 0, v[74:75]
	v_lshlrev_b32_e32 v34, 16, v108
	v_and_b32_e32 v35, 0xffff0000, v108
	v_mov_b32_e32 v36, v240
	v_mov_b32_e32 v37, v241
	v_lshlrev_b32_e32 v22, 16, v36
	v_and_b32_e32 v23, 0xffff0000, v36
	v_lshlrev_b32_e32 v26, 16, v37
	v_and_b32_e32 v27, 0xffff0000, v37
	v_mul_f32_e32 v28, 0xbfb8aa3b, v22
	v_mul_f32_e32 v29, 0xbfb8aa3b, v23
	v_mul_f32_e32 v32, 0xbfb8aa3b, v26
	v_mul_f32_e32 v33, 0xbfb8aa3b, v27
	v_exp_f32_e32 v28, v28
	v_exp_f32_e32 v29, v29
	v_exp_f32_e32 v32, v32
	v_exp_f32_e32 v33, v33
	v_add_f32_e32 v28, 1.0, v28
	v_add_f32_e32 v29, 1.0, v29
	v_add_f32_e32 v32, 1.0, v32
	v_add_f32_e32 v33, 1.0, v33
	v_rcp_f32_e32 v28, v28
	v_rcp_f32_e32 v29, v29
	v_rcp_f32_e32 v32, v32
	v_rcp_f32_e32 v33, v33
	v_pk_mul_f32 v[16:17], v[16:17], v[22:23]
	v_pk_mul_f32 v[18:19], v[18:19], v[26:27]
	v_pk_mul_f32 v[16:17], v[16:17], v[28:29]
	v_pk_mul_f32 v[18:19], v[18:19], v[32:33]
	v_cvt_pk_bf16_f32 v16, v16, v17
	v_cvt_pk_bf16_f32 v17, v18, v19
	global_store_dwordx2 v[24:25], v[16:17], off offset:1120
	v_max_f32_e32 v16, v90, v90
	v_max_f32_e32 v17, v69, v69
	v_max_f32_e32 v38, v17, v16
	v_sub_f32_e32 v16, v69, v38
	v_sub_f32_e32 v17, v90, v38
	v_max_f32_e32 v22, v104, v104
	v_exp_f32_e32 v16, v16
	v_exp_f32_e32 v17, v17
	v_max_f32_e32 v23, v102, v102
	v_max_f32_e32 v22, v38, v22
	v_max_f32_e32 v23, v22, v23
	v_mov_b32_e32 v90, v115
	v_sub_f32_e32 v38, v38, v22
	v_sub_f32_e32 v44, v104, v22
	v_sub_f32_e32 v22, v22, v23
	v_sub_f32_e32 v45, v102, v23
	v_exp_f32_e32 v99, v22
	v_lshl_add_u64 v[22:23], s[16:17], 0, v[20:21]
	v_pk_mul_f32 v[20:21], v[90:91], v[16:17]
	v_exp_f32_e32 v95, v38
	v_pk_fma_f32 v[40:41], v[90:91], v[16:17], v[20:21] op_sel_hi:[1,1,0]
	v_lshlrev_b32_e32 v18, 16, v100
	v_exp_f32_e32 v40, v44
	v_and_b32_e32 v19, 0xffff0000, v100
	v_lshlrev_b32_e32 v24, 16, v101
	v_and_b32_e32 v25, 0xffff0000, v101
	v_lshl_add_u64 v[38:39], v[22:23], 0, s[12:13]
	v_pk_mul_f32 v[42:43], v[20:21], v[18:19] op_sel:[1,0]
	v_pk_mul_f32 v[24:25], v[20:21], v[24:25] op_sel:[1,0]
	v_mov_b32_e32 v22, v95
	v_lshl_add_u64 v[18:19], v[38:39], 0, v[74:75]
	v_pk_fma_f32 v[38:39], v[12:13], v[16:17], v[42:43] op_sel_hi:[1,0,1]
	v_pk_fma_f32 v[14:15], v[14:15], v[16:17], v[24:25] op_sel_hi:[1,0,1]
	v_pk_mul_f32 v[24:25], v[22:23], v[38:39] op_sel_hi:[0,1]
	v_pk_mul_f32 v[38:39], v[22:23], v[14:15] op_sel_hi:[0,1]
	v_pk_mul_f32 v[14:15], v[94:95], v[40:41]
	v_lshlrev_b32_e32 v26, 16, v106
	v_pk_fma_f32 v[40:41], v[94:95], v[40:41], v[14:15] op_sel_hi:[1,1,0]
	v_and_b32_e32 v27, 0xffff0000, v106
	v_exp_f32_e32 v40, v45
	v_lshlrev_b32_e32 v32, 16, v107
	v_and_b32_e32 v33, 0xffff0000, v107
	v_mov_b32_e32 v12, v99
	v_pk_fma_f32 v[24:25], v[14:15], v[26:27], v[24:25] op_sel_hi:[0,1,1]
	v_pk_fma_f32 v[32:33], v[14:15], v[32:33], v[38:39] op_sel_hi:[0,1,1]
	v_pk_mul_f32 v[38:39], v[12:13], v[24:25] op_sel_hi:[0,1]
	v_pk_mul_f32 v[24:25], v[98:99], v[40:41]
	v_lshlrev_b32_e32 v36, 16, v109
	v_add_f32_e32 v13, v24, v25
	v_rcp_f32_e32 v26, v13
	v_and_b32_e32 v37, 0xffff0000, v109
	v_pk_mul_f32 v[32:33], v[12:13], v[32:33] op_sel_hi:[0,1]
	v_pk_fma_f32 v[34:35], v[24:25], v[34:35], v[38:39] op_sel_hi:[0,1,1]
	v_pk_fma_f32 v[32:33], v[24:25], v[36:37], v[32:33] op_sel_hi:[0,1,1]
	v_pk_mul_f32 v[34:35], v[26:27], v[34:35] op_sel_hi:[0,1]
	v_pk_mul_f32 v[32:33], v[26:27], v[32:33] op_sel_hi:[0,1]
	v_lshlrev_b32_e32 v42, 16, v97
	v_and_b32_e32 v43, 0xffff0000, v97
	v_mov_b32_e32 v28, v242
	v_mov_b32_e32 v29, v243
	v_lshlrev_b32_e32 v36, 16, v28
	v_and_b32_e32 v37, 0xffff0000, v28
	v_lshlrev_b32_e32 v28, 16, v29
	v_and_b32_e32 v29, 0xffff0000, v29
	v_mul_f32_e32 v13, 0xbfb8aa3b, v36
	v_mul_f32_e32 v17, 0xbfb8aa3b, v37
	v_mul_f32_e32 v23, 0xbfb8aa3b, v28
	v_mul_f32_e32 v27, 0xbfb8aa3b, v29
	v_exp_f32_e32 v13, v13
	v_exp_f32_e32 v17, v17
	v_exp_f32_e32 v23, v23
	v_exp_f32_e32 v27, v27
	v_add_f32_e32 v13, 1.0, v13
	v_add_f32_e32 v17, 1.0, v17
	v_add_f32_e32 v23, 1.0, v23
	v_add_f32_e32 v27, 1.0, v27
	v_rcp_f32_e32 v38, v13
	v_rcp_f32_e32 v39, v17
	v_rcp_f32_e32 v40, v23
	v_rcp_f32_e32 v41, v27
	v_pk_mul_f32 v[34:35], v[34:35], v[36:37]
	v_pk_mul_f32 v[28:29], v[32:33], v[28:29]
	v_pk_mul_f32 v[32:33], v[34:35], v[38:39]
	v_pk_mul_f32 v[28:29], v[28:29], v[40:41]
	v_cvt_pk_bf16_f32 v32, v32, v33
	v_cvt_pk_bf16_f32 v33, v28, v29
	global_store_dwordx2 v[18:19], v[32:33], off offset:1024
	v_lshlrev_b32_e32 v32, 16, v88
	v_and_b32_e32 v33, 0xffff0000, v88
	v_lshlrev_b32_e32 v34, 16, v89
	v_and_b32_e32 v35, 0xffff0000, v89
	v_pk_mul_f32 v[32:33], v[20:21], v[32:33] op_sel:[1,0]
	v_pk_mul_f32 v[34:35], v[20:21], v[34:35] op_sel:[1,0]
	v_pk_fma_f32 v[8:9], v[8:9], v[16:17], v[32:33] op_sel_hi:[1,0,1]
	v_pk_fma_f32 v[10:11], v[10:11], v[16:17], v[34:35] op_sel_hi:[1,0,1]
	v_lshlrev_b32_e32 v36, 16, v92
	v_and_b32_e32 v37, 0xffff0000, v92
	v_lshlrev_b32_e32 v38, 16, v93
	v_and_b32_e32 v39, 0xffff0000, v93
	v_pk_mul_f32 v[8:9], v[22:23], v[8:9] op_sel_hi:[0,1]
	v_pk_mul_f32 v[10:11], v[22:23], v[10:11] op_sel_hi:[0,1]
	v_pk_fma_f32 v[8:9], v[14:15], v[36:37], v[8:9] op_sel_hi:[0,1,1]
	v_pk_fma_f32 v[10:11], v[14:15], v[38:39], v[10:11] op_sel_hi:[0,1,1]
	v_lshlrev_b32_e32 v40, 16, v96
	v_and_b32_e32 v41, 0xffff0000, v96
	v_pk_mul_f32 v[8:9], v[12:13], v[8:9] op_sel_hi:[0,1]
	v_pk_mul_f32 v[10:11], v[12:13], v[10:11] op_sel_hi:[0,1]
	v_pk_fma_f32 v[8:9], v[24:25], v[40:41], v[8:9] op_sel_hi:[0,1,1]
	v_pk_fma_f32 v[10:11], v[24:25], v[42:43], v[10:11] op_sel_hi:[0,1,1]
	v_pk_mul_f32 v[8:9], v[26:27], v[8:9] op_sel_hi:[0,1]
	v_pk_mul_f32 v[10:11], v[26:27], v[10:11] op_sel_hi:[0,1]
	v_lshlrev_b32_e32 v38, 16, v87
	v_and_b32_e32 v39, 0xffff0000, v87
	v_mov_b32_e32 v28, v244
	v_mov_b32_e32 v29, v245
	v_lshlrev_b32_e32 v32, 16, v28
	v_and_b32_e32 v33, 0xffff0000, v28
	v_lshlrev_b32_e32 v28, 16, v29
	v_and_b32_e32 v29, 0xffff0000, v29
	v_mul_f32_e32 v13, 0xbfb8aa3b, v32
	v_mul_f32_e32 v17, 0xbfb8aa3b, v33
	v_mul_f32_e32 v23, 0xbfb8aa3b, v28
	v_mul_f32_e32 v27, 0xbfb8aa3b, v29
	v_exp_f32_e32 v13, v13
	v_exp_f32_e32 v17, v17
	v_exp_f32_e32 v23, v23
	v_exp_f32_e32 v27, v27
	v_add_f32_e32 v13, 1.0, v13
	v_add_f32_e32 v17, 1.0, v17
	v_add_f32_e32 v23, 1.0, v23
	v_add_f32_e32 v27, 1.0, v27
	v_rcp_f32_e32 v34, v13
	v_rcp_f32_e32 v35, v17
	v_rcp_f32_e32 v36, v23
	v_rcp_f32_e32 v37, v27
	v_pk_mul_f32 v[8:9], v[8:9], v[32:33]
	v_pk_mul_f32 v[10:11], v[10:11], v[28:29]
	v_pk_mul_f32 v[8:9], v[8:9], v[34:35]
	v_pk_mul_f32 v[10:11], v[10:11], v[36:37]
	v_cvt_pk_bf16_f32 v8, v8, v9
	v_cvt_pk_bf16_f32 v9, v10, v11
	global_store_dwordx2 v[18:19], v[8:9], off offset:1056
	v_lshlrev_b32_e32 v10, 16, v82
	v_and_b32_e32 v11, 0xffff0000, v82
	v_lshlrev_b32_e32 v28, 16, v83
	v_and_b32_e32 v29, 0xffff0000, v83
	v_pk_mul_f32 v[10:11], v[20:21], v[10:11] op_sel:[1,0]
	v_pk_mul_f32 v[28:29], v[20:21], v[28:29] op_sel:[1,0]
	v_pk_fma_f32 v[4:5], v[4:5], v[16:17], v[10:11] op_sel_hi:[1,0,1]
	v_pk_fma_f32 v[6:7], v[6:7], v[16:17], v[28:29] op_sel_hi:[1,0,1]
	v_lshlrev_b32_e32 v32, 16, v84
	v_and_b32_e32 v33, 0xffff0000, v84
	v_lshlrev_b32_e32 v34, 16, v85
	v_and_b32_e32 v35, 0xffff0000, v85
	v_pk_mul_f32 v[4:5], v[22:23], v[4:5] op_sel_hi:[0,1]
	v_pk_mul_f32 v[6:7], v[22:23], v[6:7] op_sel_hi:[0,1]
	v_pk_fma_f32 v[4:5], v[14:15], v[32:33], v[4:5] op_sel_hi:[0,1,1]
	v_pk_fma_f32 v[6:7], v[14:15], v[34:35], v[6:7] op_sel_hi:[0,1,1]
	v_lshlrev_b32_e32 v36, 16, v86
	v_and_b32_e32 v37, 0xffff0000, v86
	v_pk_mul_f32 v[4:5], v[12:13], v[4:5] op_sel_hi:[0,1]
	v_pk_mul_f32 v[6:7], v[12:13], v[6:7] op_sel_hi:[0,1]
	v_pk_fma_f32 v[4:5], v[24:25], v[36:37], v[4:5] op_sel_hi:[0,1,1]
	v_pk_fma_f32 v[6:7], v[24:25], v[38:39], v[6:7] op_sel_hi:[0,1,1]
	v_pk_mul_f32 v[4:5], v[26:27], v[4:5] op_sel_hi:[0,1]
	v_pk_mul_f32 v[6:7], v[26:27], v[6:7] op_sel_hi:[0,1]
	v_mov_b32_e32 v8, v246
	v_mov_b32_e32 v9, v247
	v_lshlrev_b32_e32 v10, 16, v8
	v_and_b32_e32 v11, 0xffff0000, v8
	v_lshlrev_b32_e32 v8, 16, v9
	v_and_b32_e32 v9, 0xffff0000, v9
	v_mul_f32_e32 v13, 0xbfb8aa3b, v10
	v_mul_f32_e32 v17, 0xbfb8aa3b, v11
	v_mul_f32_e32 v23, 0xbfb8aa3b, v8
	v_mul_f32_e32 v27, 0xbfb8aa3b, v9
	v_exp_f32_e32 v13, v13
	v_exp_f32_e32 v17, v17
	v_exp_f32_e32 v23, v23
	v_exp_f32_e32 v27, v27
	v_add_f32_e32 v13, 1.0, v13
	v_add_f32_e32 v17, 1.0, v17
	v_add_f32_e32 v23, 1.0, v23
	v_add_f32_e32 v27, 1.0, v27
	v_rcp_f32_e32 v28, v13
	v_rcp_f32_e32 v29, v17
	v_rcp_f32_e32 v32, v23
	v_rcp_f32_e32 v33, v27
	v_pk_mul_f32 v[4:5], v[4:5], v[10:11]
	v_pk_mul_f32 v[6:7], v[6:7], v[8:9]
	v_pk_mul_f32 v[4:5], v[4:5], v[28:29]
	v_pk_mul_f32 v[6:7], v[6:7], v[32:33]
	v_cvt_pk_bf16_f32 v4, v4, v5
	v_cvt_pk_bf16_f32 v5, v6, v7
	global_store_dwordx2 v[18:19], v[4:5], off offset:1088
	v_lshlrev_b32_e32 v6, 16, v76
	v_and_b32_e32 v7, 0xffff0000, v76
	v_pk_mul_f32 v[6:7], v[20:21], v[6:7] op_sel:[1,0]
	v_lshlrev_b32_e32 v8, 16, v77
	v_and_b32_e32 v9, 0xffff0000, v77
	v_pk_fma_f32 v[0:1], v[0:1], v[16:17], v[6:7] op_sel_hi:[1,0,1]
	v_lshlrev_b32_e32 v10, 16, v80
	v_and_b32_e32 v11, 0xffff0000, v80
	v_pk_mul_f32 v[8:9], v[20:21], v[8:9] op_sel:[1,0]
	v_pk_mul_f32 v[0:1], v[22:23], v[0:1] op_sel_hi:[0,1]
	v_pk_fma_f32 v[2:3], v[2:3], v[16:17], v[8:9] op_sel_hi:[1,0,1]
	v_pk_fma_f32 v[0:1], v[14:15], v[10:11], v[0:1] op_sel_hi:[0,1,1]
	v_lshlrev_b32_e32 v28, 16, v81
	v_and_b32_e32 v29, 0xffff0000, v81
	v_pk_mul_f32 v[2:3], v[22:23], v[2:3] op_sel_hi:[0,1]
	v_pk_fma_f32 v[2:3], v[14:15], v[28:29], v[2:3] op_sel_hi:[0,1,1]
	v_lshlrev_b32_e32 v30, 16, v78
	v_and_b32_e32 v31, 0xffff0000, v78
	v_lshlrev_b32_e32 v32, 16, v79
	v_and_b32_e32 v33, 0xffff0000, v79
	v_pk_mul_f32 v[0:1], v[12:13], v[0:1] op_sel_hi:[0,1]
	v_pk_mul_f32 v[2:3], v[12:13], v[2:3] op_sel_hi:[0,1]
	v_pk_fma_f32 v[0:1], v[24:25], v[30:31], v[0:1] op_sel_hi:[0,1,1]
	v_pk_fma_f32 v[2:3], v[24:25], v[32:33], v[2:3] op_sel_hi:[0,1,1]
	v_pk_mul_f32 v[0:1], v[26:27], v[0:1] op_sel_hi:[0,1]
	v_pk_mul_f32 v[2:3], v[26:27], v[2:3] op_sel_hi:[0,1]
	v_mov_b32_e32 v4, v248
	v_mov_b32_e32 v5, v249
	v_lshlrev_b32_e32 v6, 16, v4
	v_and_b32_e32 v7, 0xffff0000, v4
	v_lshlrev_b32_e32 v4, 16, v5
	v_and_b32_e32 v5, 0xffff0000, v5
	v_mul_f32_e32 v8, 0xbfb8aa3b, v6
	v_mul_f32_e32 v9, 0xbfb8aa3b, v7
	v_mul_f32_e32 v10, 0xbfb8aa3b, v4
	v_mul_f32_e32 v11, 0xbfb8aa3b, v5
	v_exp_f32_e32 v8, v8
	v_exp_f32_e32 v9, v9
	v_exp_f32_e32 v10, v10
	v_exp_f32_e32 v11, v11
	v_add_f32_e32 v8, 1.0, v8
	v_add_f32_e32 v9, 1.0, v9
	v_add_f32_e32 v10, 1.0, v10
	v_add_f32_e32 v11, 1.0, v11
	v_rcp_f32_e32 v8, v8
	v_rcp_f32_e32 v9, v9
	v_rcp_f32_e32 v10, v10
	v_rcp_f32_e32 v11, v11
	v_pk_mul_f32 v[0:1], v[0:1], v[6:7]
	v_pk_mul_f32 v[2:3], v[2:3], v[4:5]
	v_pk_mul_f32 v[0:1], v[0:1], v[8:9]
	v_pk_mul_f32 v[2:3], v[2:3], v[10:11]
	v_cvt_pk_bf16_f32 v0, v0, v1
	v_cvt_pk_bf16_f32 v1, v2, v3
	global_store_dwordx2 v[18:19], v[0:1], off offset:1120
	s_cbranch_scc0 .LBB0_298
.LBB0_278:
	s_ashr_i32 s14, s23, 4
	s_and_b32 s12, s23, 15
	s_min_u32 s74, s12, 3
	s_ashr_i32 s15, s14, 31
	s_lshl_b64 s[0:1], s[14:15], 12
	s_lshl_b32 s24, s12, 8
	s_or_b32 s16, s0, s24
	s_mov_b32 s17, s1
	s_lshl_b64 s[16:17], s[16:17], 7
	s_add_u32 s18, s66, s16
	s_addc_u32 s19, s67, s17
	s_lshl_b64 s[20:21], s[14:15], 19
	s_add_u32 s15, s68, s20
	s_addc_u32 s21, s69, s21
	s_lshl_b32 s20, s12, 9
	s_add_u32 s20, s15, s20
	s_addc_u32 s21, s21, 0
	v_mov_b32_e32 v65, v121
	v_mov_b32_e32 v69, v121
	v_lshl_add_u64 v[0:1], s[18:19], 0, v[56:57]
	v_lshl_add_u64 v[2:3], s[18:19], 0, v[60:61]
	v_lshl_add_u64 v[8:9], s[18:19], 0, v[62:63]
	v_lshl_add_u64 v[10:11], s[18:19], 0, v[120:121]
	v_lshl_add_u64 v[16:17], s[20:21], 0, v[64:65]
	v_mov_b32_e32 v67, v121
	v_lshl_add_u64 v[18:19], s[20:21], 0, v[68:69]
	v_lshl_add_u64 v[0:1], v[0:1], 0, v[58:59]
	v_lshl_add_u64 v[4:5], v[2:3], 0, v[58:59]
	v_lshl_add_u64 v[8:9], v[8:9], 0, v[58:59]
	v_lshl_add_u64 v[12:13], v[10:11], 0, v[58:59]
	v_lshl_add_u64 v[16:17], v[16:17], 0, v[66:67]
	v_lshl_add_u64 v[20:21], v[18:19], 0, v[66:67]
	v_mov_b32_e32 v71, v121
	v_mov_b32_e32 v73, v121
	s_ashr_i32 s26, s23, 7
	s_ashr_i32 s27, s26, 31
	s_lshl_b64 s[26:27], s[26:27], 22
	v_add_u32_e32 v250, s24, v48
	v_lshlrev_b32_e32 v250, 10, v250
	v_mov_b32_e32 v251, v121
	v_lshl_add_u64 v[250:251], s[26:27], 0, v[250:251]
	v_lshlrev_b64 v[250:251], 1, v[250:251]
	s_lshl_b32 s26, s14, 7
	v_lshl_add_u64 v[250:251], s[70:71], 0, v[250:251]
	s_and_b32 s26, s26, 0x380
	s_mov_b32 s27, 0
	v_lshl_add_u64 v[250:251], v[250:251], 0, s[26:27]
	v_mov_b32_e32 v252, v74
	v_mov_b32_e32 v253, v121
	v_lshl_add_u64 v[250:251], v[250:251], 0, v[252:253]
	s_mov_b64 s[72:73], 0x8000
	global_load_dwordx2 v[234:235], v[250:251], off offset:1024
	global_load_dwordx2 v[236:237], v[250:251], off offset:1056
	global_load_dwordx2 v[238:239], v[250:251], off offset:1088
	global_load_dwordx2 v[240:241], v[250:251], off offset:1120
	v_lshl_add_u64 v[250:251], v[250:251], 0, s[72:73]
	global_load_dwordx2 v[242:243], v[250:251], off offset:1024
	global_load_dwordx2 v[244:245], v[250:251], off offset:1056
	global_load_dwordx2 v[246:247], v[250:251], off offset:1088
	global_load_dwordx2 v[248:249], v[250:251], off offset:1120
	global_load_dwordx4 v[0:3], v[0:1], off
	s_nop 0
	global_load_dwordx4 v[4:7], v[4:5], off
	s_nop 0
	global_load_dwordx4 v[8:11], v[8:9], off
	s_nop 0
	global_load_dwordx4 v[12:15], v[12:13], off
	s_nop 0
	global_load_dwordx4 v[16:19], v[16:17], off
	s_nop 0
	global_load_dwordx4 v[36:39], v[20:21], off
	v_lshl_add_u64 v[20:21], s[20:21], 0, v[70:71]
	v_lshl_add_u64 v[22:23], s[20:21], 0, v[72:73]
	v_lshl_add_u64 v[20:21], v[20:21], 0, v[66:67]
	v_lshl_add_u64 v[22:23], v[22:23], 0, v[66:67]
	v_lshl_add_u64 v[32:33], v[50:51], 0, s[16:17]
	global_load_dwordx4 v[40:43], v[20:21], off
	global_load_dwordx4 v[44:47], v[22:23], off
	s_nop 0
	global_load_dwordx4 v[20:23], v[32:33], off
	global_load_dwordx4 v[24:27], v[32:33], off offset:64
	global_load_dwordx4 v[28:31], v[32:33], off offset:2048
	s_nop 0
	global_load_dwordx4 v[32:35], v[32:33], off offset:2112
	v_add_u32_e32 v140, s24, v48
	v_mov_b32_e32 v141, v121
	s_cmp_lg_u32 s12, 0
	v_lshl_add_u64 v[76:77], s[0:1], 0, v[140:141]
	v_mov_b64_e32 v[110:111], 0
	s_cselect_b64 s[18:19], -1, 0
	s_cmp_eq_u32 s12, 0
	v_mov_b64_e32 v[112:113], 0
	v_mov_b64_e32 v[118:119], 0
	v_mov_b64_e32 v[128:129], 0
	v_mov_b64_e32 v[142:143], 0
	v_mov_b32_e32 v132, 0xf149f2ca
	v_mov_b32_e32 v133, 0
	s_cbranch_scc1 .LBB0_280
	v_mad_u64_u32 v[78:79], s[16:17], v76, 24, s[42:43]
	v_mad_i32_i24 v79, v77, 24, v79
	global_load_dwordx2 v[132:133], v[78:79], off
	v_mad_u64_u32 v[78:79], s[16:17], v76, s4, v[52:53]
	v_mad_i32_i24 v79, v77, s4, v79
	global_load_dwordx2 v[142:143], v[78:79], off
	global_load_dwordx2 v[128:129], v[78:79], off offset:32
	global_load_dwordx2 v[118:119], v[78:79], off offset:64
	global_load_dwordx2 v[112:113], v[78:79], off offset:96
